# in/up GEMM epilogues: the 8 per-row sum-of-squares loads of a tile issued together (no store drain between row groups)
# speedup vs baseline: 1.0066x; 1.0029x over previous
.LBB0_216:
	v_lshl_add_u32 v144, s40, 8, v156
	v_ashrrev_i32_e32 v145, 31, v144
	v_lshl_add_u64 v[146:147], v[144:145], 2, s[44:45]
	global_load_dword v141, v[146:147], off
	global_load_dword v164, v[146:147], off offset:64
	global_load_dword v165, v[146:147], off offset:128
	global_load_dword v166, v[146:147], off offset:192
	global_load_dword v167, v[146:147], off offset:512
	global_load_dword v168, v[146:147], off offset:576
	global_load_dword v169, v[146:147], off offset:640
	global_load_dword v170, v[146:147], off offset:704
	v_lshl_or_b32 v142, s30, 8, v158
	v_ashrrev_i32_e32 v143, 31, v142
	s_cmp_lg_u64 s[22:23], 0
	v_add_u32_e32 v140, s31, v142
	s_cselect_b64 s[42:43], -1, 0
	s_cmp_eq_u64 s[22:23], 0
	s_waitcnt vmcnt(0)
	v_fmamk_f32 v141, v141, 0x3a800000, v235
	v_cmp_gt_f32_e32 vcc, s73, v141
	v_mul_f32_e32 v148, 0x4f800000, v141
	s_nop 0
	v_cndmask_b32_e32 v141, v141, v148, vcc
	v_sqrt_f32_e32 v148, v141
	s_nop 0
	v_add_u32_e32 v149, -1, v148
	v_fma_f32 v150, -v149, v148, v141
	v_cmp_ge_f32_e64 s[40:41], 0, v150
	v_add_u32_e32 v150, 1, v148
	s_nop 0
	v_cndmask_b32_e64 v149, v148, v149, s[40:41]
	v_fma_f32 v148, -v150, v148, v141
	v_cmp_lt_f32_e64 s[40:41], 0, v148
	s_nop 1
	v_cndmask_b32_e64 v148, v149, v150, s[40:41]
	v_mul_f32_e32 v149, 0x37800000, v148
	v_cndmask_b32_e32 v148, v148, v149, vcc
	v_cmp_class_f32_e32 vcc, v141, v236
	s_nop 1
	v_cndmask_b32_e32 v141, v148, v141, vcc
	v_div_scale_f32 v148, s[10:11], v141, v141, 1.0
	v_rcp_f32_e32 v149, v148
	s_nop 0
	v_fma_f32 v150, -v148, v149, 1.0
	v_fmac_f32_e32 v149, v150, v149
	v_div_scale_f32 v150, vcc, 1.0, v141, 1.0
	v_mul_f32_e32 v151, v150, v149
	v_fma_f32 v152, -v148, v151, v150
	v_fmac_f32_e32 v151, v152, v149
	v_fma_f32 v148, -v148, v151, v150
	v_add_u32_e32 v152, s9, v144
	v_div_fmas_f32 v148, v148, v149, v151
	v_mov_b64_e32 v[150:151], s[20:21]
	v_ashrrev_i32_e32 v153, 31, v152
	v_div_fixup_f32 v148, v148, v141, 1.0
	v_mad_i64_i32 v[150:151], s[10:11], v144, s84, v[150:151]
	v_lshlrev_b64 v[152:153], 11, v[152:153]
	v_lshl_add_u64 v[150:151], v[142:143], 1, v[150:151]
	v_lshl_add_u64 v[152:153], s[22:23], 0, v[152:153]
	v_pk_mul_f32 v[126:127], v[126:127], v[148:149] op_sel_hi:[1,0]
	v_pk_mul_f32 v[124:125], v[124:125], v[148:149] op_sel_hi:[1,0]
	v_pk_mul_f32 v[122:123], v[122:123], v[148:149] op_sel_hi:[1,0]
	v_pk_mul_f32 v[120:121], v[120:121], v[148:149] op_sel_hi:[1,0]
	v_ashrrev_i32_e32 v141, 31, v140
	v_cvt_pk_bf16_f32 v160, v124, v125
	v_cvt_pk_bf16_f32 v161, v126, v127
	v_cvt_pk_bf16_f32 v162, v120, v121
	v_cvt_pk_bf16_f32 v163, v122, v123
	global_store_dwordx4 v[150:151], v[160:163], off
	s_cbranch_scc1 .LBB0_218
	s_nop 0
	v_lshl_add_u64 v[160:161], v[140:141], 2, v[152:153]
	global_store_dwordx4 v[160:161], v[124:127], off nt
	global_store_dwordx4 v[160:161], v[120:123], off offset:16 nt

.LBB0_222:
	s_nop 1
	v_mov_b32_e32 v113, v164
	s_nop 0
	v_or_b32_e32 v112, 16, v144
	v_fmamk_f32 v113, v113, 0x3a800000, v235
	v_cmp_gt_f32_e32 vcc, s73, v113
	v_mul_f32_e32 v114, 0x4f800000, v113
	s_nop 0
	v_cndmask_b32_e32 v113, v113, v114, vcc
	v_sqrt_f32_e32 v114, v113
	s_nop 0
	v_add_u32_e32 v115, -1, v114
	v_fma_f32 v116, -v115, v114, v113
	v_cmp_ge_f32_e64 s[42:43], 0, v116
	v_add_u32_e32 v116, 1, v114
	s_nop 0
	v_cndmask_b32_e64 v115, v114, v115, s[42:43]
	v_fma_f32 v114, -v116, v114, v113
	v_cmp_lt_f32_e64 s[42:43], 0, v114
	s_nop 1
	v_cndmask_b32_e64 v114, v115, v116, s[42:43]
	v_mul_f32_e32 v115, 0x37800000, v114
	v_cndmask_b32_e32 v114, v114, v115, vcc
	v_cmp_class_f32_e32 vcc, v113, v236
	s_nop 1
	v_cndmask_b32_e32 v113, v114, v113, vcc
	v_div_scale_f32 v114, s[10:11], v113, v113, 1.0
	v_rcp_f32_e32 v115, v114
	s_nop 0
	v_fma_f32 v116, -v114, v115, 1.0
	v_fmac_f32_e32 v115, v116, v115
	v_div_scale_f32 v116, vcc, 1.0, v113, 1.0
	v_mul_f32_e32 v117, v116, v115
	v_fma_f32 v118, -v114, v117, v116
	v_fmac_f32_e32 v117, v118, v115
	v_fma_f32 v114, -v114, v117, v116
	v_add_u32_e32 v118, s9, v112
	v_div_fmas_f32 v114, v114, v115, v117
	v_mov_b64_e32 v[116:117], s[20:21]
	v_ashrrev_i32_e32 v119, 31, v118
	v_div_fixup_f32 v114, v114, v113, 1.0
	v_mad_i64_i32 v[116:117], s[10:11], v112, s84, v[116:117]
	v_lshlrev_b64 v[118:119], 11, v[118:119]
	v_lshl_add_u64 v[116:117], v[142:143], 1, v[116:117]
	v_lshl_add_u64 v[118:119], s[22:23], 0, v[118:119]
	v_pk_mul_f32 v[110:111], v[110:111], v[114:115] op_sel_hi:[1,0]
	v_pk_mul_f32 v[108:109], v[108:109], v[114:115] op_sel_hi:[1,0]
	v_pk_mul_f32 v[106:107], v[106:107], v[114:115] op_sel_hi:[1,0]
	v_pk_mul_f32 v[104:105], v[104:105], v[114:115] op_sel_hi:[1,0]
	s_and_b64 vcc, exec, s[40:41]
	v_cvt_pk_bf16_f32 v120, v108, v109
	v_cvt_pk_bf16_f32 v121, v110, v111
	v_cvt_pk_bf16_f32 v122, v104, v105
	v_cvt_pk_bf16_f32 v123, v106, v107
	global_store_dwordx4 v[116:117], v[120:123], off
	s_cbranch_vccnz .LBB0_224
	s_nop 0
	v_lshl_add_u64 v[120:121], v[140:141], 2, v[118:119]
	global_store_dwordx4 v[120:121], v[108:111], off nt
	global_store_dwordx4 v[120:121], v[104:107], off offset:16 nt

.LBB0_228:
	s_nop 1
	v_mov_b32_e32 v97, v165
	s_nop 0
	v_or_b32_e32 v96, 32, v144
	v_fmamk_f32 v97, v97, 0x3a800000, v235
	v_cmp_gt_f32_e32 vcc, s73, v97
	v_mul_f32_e32 v98, 0x4f800000, v97
	s_nop 0
	v_cndmask_b32_e32 v97, v97, v98, vcc
	v_sqrt_f32_e32 v98, v97
	s_nop 0
	v_add_u32_e32 v99, -1, v98
	v_fma_f32 v100, -v99, v98, v97
	v_cmp_ge_f32_e64 s[42:43], 0, v100
	v_add_u32_e32 v100, 1, v98
	s_nop 0
	v_cndmask_b32_e64 v99, v98, v99, s[42:43]
	v_fma_f32 v98, -v100, v98, v97
	v_cmp_lt_f32_e64 s[42:43], 0, v98
	s_nop 1
	v_cndmask_b32_e64 v98, v99, v100, s[42:43]
	v_mul_f32_e32 v99, 0x37800000, v98
	v_cndmask_b32_e32 v98, v98, v99, vcc
	v_cmp_class_f32_e32 vcc, v97, v236
	s_nop 1
	v_cndmask_b32_e32 v97, v98, v97, vcc
	v_div_scale_f32 v98, s[10:11], v97, v97, 1.0
	v_rcp_f32_e32 v99, v98
	s_nop 0
	v_fma_f32 v100, -v98, v99, 1.0
	v_fmac_f32_e32 v99, v100, v99
	v_div_scale_f32 v100, vcc, 1.0, v97, 1.0
	v_mul_f32_e32 v101, v100, v99
	v_fma_f32 v102, -v98, v101, v100
	v_fmac_f32_e32 v101, v102, v99
	v_fma_f32 v98, -v98, v101, v100
	v_add_u32_e32 v102, s9, v96
	v_div_fmas_f32 v98, v98, v99, v101
	v_mov_b64_e32 v[100:101], s[20:21]
	v_ashrrev_i32_e32 v103, 31, v102
	v_div_fixup_f32 v98, v98, v97, 1.0
	v_mad_i64_i32 v[100:101], s[10:11], v96, s84, v[100:101]
	v_lshlrev_b64 v[102:103], 11, v[102:103]
	v_lshl_add_u64 v[100:101], v[142:143], 1, v[100:101]
	v_lshl_add_u64 v[102:103], s[22:23], 0, v[102:103]
	v_pk_mul_f32 v[94:95], v[94:95], v[98:99] op_sel_hi:[1,0]
	v_pk_mul_f32 v[92:93], v[92:93], v[98:99] op_sel_hi:[1,0]
	v_pk_mul_f32 v[90:91], v[90:91], v[98:99] op_sel_hi:[1,0]
	v_pk_mul_f32 v[88:89], v[88:89], v[98:99] op_sel_hi:[1,0]
	s_and_b64 vcc, exec, s[40:41]
	v_cvt_pk_bf16_f32 v104, v92, v93
	v_cvt_pk_bf16_f32 v105, v94, v95
	v_cvt_pk_bf16_f32 v106, v88, v89
	v_cvt_pk_bf16_f32 v107, v90, v91
	global_store_dwordx4 v[100:101], v[104:107], off
	s_cbranch_vccnz .LBB0_230
	s_nop 0
	v_lshl_add_u64 v[104:105], v[140:141], 2, v[102:103]
	global_store_dwordx4 v[104:105], v[92:95], off nt
	global_store_dwordx4 v[104:105], v[88:91], off offset:16 nt

.LBB0_234:
	s_nop 1
	v_mov_b32_e32 v81, v166
	s_nop 0
	v_or_b32_e32 v80, 48, v144
	v_fmamk_f32 v81, v81, 0x3a800000, v235
	v_cmp_gt_f32_e32 vcc, s73, v81
	v_mul_f32_e32 v82, 0x4f800000, v81
	s_nop 0
	v_cndmask_b32_e32 v81, v81, v82, vcc
	v_sqrt_f32_e32 v82, v81
	s_nop 0
	v_add_u32_e32 v83, -1, v82
	v_fma_f32 v84, -v83, v82, v81
	v_cmp_ge_f32_e64 s[42:43], 0, v84
	v_add_u32_e32 v84, 1, v82
	s_nop 0
	v_cndmask_b32_e64 v83, v82, v83, s[42:43]
	v_fma_f32 v82, -v84, v82, v81
	v_cmp_lt_f32_e64 s[42:43], 0, v82
	s_nop 1
	v_cndmask_b32_e64 v82, v83, v84, s[42:43]
	v_mul_f32_e32 v83, 0x37800000, v82
	v_cndmask_b32_e32 v82, v82, v83, vcc
	v_cmp_class_f32_e32 vcc, v81, v236
	s_nop 1
	v_cndmask_b32_e32 v81, v82, v81, vcc
	v_div_scale_f32 v82, s[10:11], v81, v81, 1.0
	v_rcp_f32_e32 v83, v82
	s_nop 0
	v_fma_f32 v84, -v82, v83, 1.0
	v_fmac_f32_e32 v83, v84, v83
	v_div_scale_f32 v84, vcc, 1.0, v81, 1.0
	v_mul_f32_e32 v85, v84, v83
	v_fma_f32 v86, -v82, v85, v84
	v_fmac_f32_e32 v85, v86, v83
	v_fma_f32 v82, -v82, v85, v84
	v_add_u32_e32 v86, s9, v80
	v_div_fmas_f32 v82, v82, v83, v85
	v_mov_b64_e32 v[84:85], s[20:21]
	v_ashrrev_i32_e32 v87, 31, v86
	v_div_fixup_f32 v82, v82, v81, 1.0
	v_mad_i64_i32 v[84:85], s[10:11], v80, s84, v[84:85]
	v_lshlrev_b64 v[86:87], 11, v[86:87]
	v_lshl_add_u64 v[84:85], v[142:143], 1, v[84:85]
	v_lshl_add_u64 v[86:87], s[22:23], 0, v[86:87]
	v_pk_mul_f32 v[78:79], v[78:79], v[82:83] op_sel_hi:[1,0]
	v_pk_mul_f32 v[76:77], v[76:77], v[82:83] op_sel_hi:[1,0]
	v_pk_mul_f32 v[74:75], v[74:75], v[82:83] op_sel_hi:[1,0]
	v_pk_mul_f32 v[72:73], v[72:73], v[82:83] op_sel_hi:[1,0]
	s_and_b64 vcc, exec, s[40:41]
	v_cvt_pk_bf16_f32 v88, v76, v77
	v_cvt_pk_bf16_f32 v89, v78, v79
	v_cvt_pk_bf16_f32 v90, v72, v73
	v_cvt_pk_bf16_f32 v91, v74, v75
	global_store_dwordx4 v[84:85], v[88:91], off
	s_cbranch_vccnz .LBB0_236
	s_nop 0
	v_lshl_add_u64 v[88:89], v[140:141], 2, v[86:87]
	global_store_dwordx4 v[88:89], v[76:79], off nt
	global_store_dwordx4 v[88:89], v[72:75], off offset:16 nt

.LBB0_240:
	s_nop 1
	v_mov_b32_e32 v65, v167
	s_nop 0
	v_add_u32_e32 v64, 0x80, v144
	v_fmamk_f32 v65, v65, 0x3a800000, v235
	v_cmp_gt_f32_e32 vcc, s73, v65
	v_mul_f32_e32 v66, 0x4f800000, v65
	s_nop 0
	v_cndmask_b32_e32 v65, v65, v66, vcc
	v_sqrt_f32_e32 v66, v65
	s_nop 0
	v_add_u32_e32 v67, -1, v66
	v_fma_f32 v68, -v67, v66, v65
	v_cmp_ge_f32_e64 s[42:43], 0, v68
	v_add_u32_e32 v68, 1, v66
	s_nop 0
	v_cndmask_b32_e64 v67, v66, v67, s[42:43]
	v_fma_f32 v66, -v68, v66, v65
	v_cmp_lt_f32_e64 s[42:43], 0, v66
	s_nop 1
	v_cndmask_b32_e64 v66, v67, v68, s[42:43]
	v_mul_f32_e32 v67, 0x37800000, v66
	v_cndmask_b32_e32 v66, v66, v67, vcc
	v_cmp_class_f32_e32 vcc, v65, v236
	s_nop 1
	v_cndmask_b32_e32 v65, v66, v65, vcc
	v_div_scale_f32 v66, s[10:11], v65, v65, 1.0
	v_rcp_f32_e32 v67, v66
	s_nop 0
	v_fma_f32 v68, -v66, v67, 1.0
	v_fmac_f32_e32 v67, v68, v67
	v_div_scale_f32 v68, vcc, 1.0, v65, 1.0
	v_mul_f32_e32 v69, v68, v67
	v_fma_f32 v70, -v66, v69, v68
	v_fmac_f32_e32 v69, v70, v67
	v_fma_f32 v66, -v66, v69, v68
	v_add_u32_e32 v70, s9, v64
	v_div_fmas_f32 v66, v66, v67, v69
	v_mov_b64_e32 v[68:69], s[20:21]
	v_ashrrev_i32_e32 v71, 31, v70
	v_div_fixup_f32 v66, v66, v65, 1.0
	v_mad_i64_i32 v[68:69], s[10:11], v64, s84, v[68:69]
	v_lshlrev_b64 v[70:71], 11, v[70:71]
	v_lshl_add_u64 v[68:69], v[142:143], 1, v[68:69]
	v_lshl_add_u64 v[70:71], s[22:23], 0, v[70:71]
	v_pk_mul_f32 v[62:63], v[62:63], v[66:67] op_sel_hi:[1,0]
	v_pk_mul_f32 v[60:61], v[60:61], v[66:67] op_sel_hi:[1,0]
	v_pk_mul_f32 v[58:59], v[58:59], v[66:67] op_sel_hi:[1,0]
	v_pk_mul_f32 v[56:57], v[56:57], v[66:67] op_sel_hi:[1,0]
	s_and_b64 vcc, exec, s[40:41]
	v_cvt_pk_bf16_f32 v72, v60, v61
	v_cvt_pk_bf16_f32 v73, v62, v63
	v_cvt_pk_bf16_f32 v74, v56, v57
	v_cvt_pk_bf16_f32 v75, v58, v59
	global_store_dwordx4 v[68:69], v[72:75], off
	s_cbranch_vccnz .LBB0_242
	s_nop 0
	v_lshl_add_u64 v[72:73], v[140:141], 2, v[70:71]
	global_store_dwordx4 v[72:73], v[60:63], off nt
	global_store_dwordx4 v[72:73], v[56:59], off offset:16 nt

.LBB0_246:
	s_nop 1
	v_mov_b32_e32 v49, v168
	s_nop 0
	v_add_u32_e32 v48, 0x90, v144
	v_fmamk_f32 v49, v49, 0x3a800000, v235
	v_cmp_gt_f32_e32 vcc, s73, v49
	v_mul_f32_e32 v50, 0x4f800000, v49
	s_nop 0
	v_cndmask_b32_e32 v49, v49, v50, vcc
	v_sqrt_f32_e32 v50, v49
	s_nop 0
	v_add_u32_e32 v51, -1, v50
	v_fma_f32 v52, -v51, v50, v49
	v_cmp_ge_f32_e64 s[42:43], 0, v52
	v_add_u32_e32 v52, 1, v50
	s_nop 0
	v_cndmask_b32_e64 v51, v50, v51, s[42:43]
	v_fma_f32 v50, -v52, v50, v49
	v_cmp_lt_f32_e64 s[42:43], 0, v50
	s_nop 1
	v_cndmask_b32_e64 v50, v51, v52, s[42:43]
	v_mul_f32_e32 v51, 0x37800000, v50
	v_cndmask_b32_e32 v50, v50, v51, vcc
	v_cmp_class_f32_e32 vcc, v49, v236
	s_nop 1
	v_cndmask_b32_e32 v49, v50, v49, vcc
	v_div_scale_f32 v50, s[10:11], v49, v49, 1.0
	v_rcp_f32_e32 v51, v50
	s_nop 0
	v_fma_f32 v52, -v50, v51, 1.0
	v_fmac_f32_e32 v51, v52, v51
	v_div_scale_f32 v52, vcc, 1.0, v49, 1.0
	v_mul_f32_e32 v53, v52, v51
	v_fma_f32 v54, -v50, v53, v52
	v_fmac_f32_e32 v53, v54, v51
	v_fma_f32 v50, -v50, v53, v52
	v_add_u32_e32 v54, s9, v48
	v_div_fmas_f32 v50, v50, v51, v53
	v_mov_b64_e32 v[52:53], s[20:21]
	v_ashrrev_i32_e32 v55, 31, v54
	v_div_fixup_f32 v50, v50, v49, 1.0
	v_mad_i64_i32 v[52:53], s[10:11], v48, s84, v[52:53]
	v_lshlrev_b64 v[54:55], 11, v[54:55]
	v_lshl_add_u64 v[52:53], v[142:143], 1, v[52:53]
	v_lshl_add_u64 v[54:55], s[22:23], 0, v[54:55]
	v_pk_mul_f32 v[46:47], v[46:47], v[50:51] op_sel_hi:[1,0]
	v_pk_mul_f32 v[44:45], v[44:45], v[50:51] op_sel_hi:[1,0]
	v_pk_mul_f32 v[42:43], v[42:43], v[50:51] op_sel_hi:[1,0]
	v_pk_mul_f32 v[40:41], v[40:41], v[50:51] op_sel_hi:[1,0]
	s_and_b64 vcc, exec, s[40:41]
	v_cvt_pk_bf16_f32 v56, v44, v45
	v_cvt_pk_bf16_f32 v57, v46, v47
	v_cvt_pk_bf16_f32 v58, v40, v41
	v_cvt_pk_bf16_f32 v59, v42, v43
	global_store_dwordx4 v[52:53], v[56:59], off
	s_cbranch_vccnz .LBB0_248
	s_nop 0
	v_lshl_add_u64 v[56:57], v[140:141], 2, v[54:55]
	global_store_dwordx4 v[56:57], v[44:47], off nt
	global_store_dwordx4 v[56:57], v[40:43], off offset:16 nt

.LBB0_252:
	s_nop 1
	v_mov_b32_e32 v33, v169
	s_nop 0
	v_add_u32_e32 v32, 0xa0, v144
	v_fmamk_f32 v33, v33, 0x3a800000, v235
	v_cmp_gt_f32_e32 vcc, s73, v33
	v_mul_f32_e32 v34, 0x4f800000, v33
	s_nop 0
	v_cndmask_b32_e32 v33, v33, v34, vcc
	v_sqrt_f32_e32 v34, v33
	s_nop 0
	v_add_u32_e32 v35, -1, v34
	v_fma_f32 v36, -v35, v34, v33
	v_cmp_ge_f32_e64 s[42:43], 0, v36
	v_add_u32_e32 v36, 1, v34
	s_nop 0
	v_cndmask_b32_e64 v35, v34, v35, s[42:43]
	v_fma_f32 v34, -v36, v34, v33
	v_cmp_lt_f32_e64 s[42:43], 0, v34
	s_nop 1
	v_cndmask_b32_e64 v34, v35, v36, s[42:43]
	v_mul_f32_e32 v35, 0x37800000, v34
	v_cndmask_b32_e32 v34, v34, v35, vcc
	v_cmp_class_f32_e32 vcc, v33, v236
	s_nop 1
	v_cndmask_b32_e32 v33, v34, v33, vcc
	v_div_scale_f32 v34, s[10:11], v33, v33, 1.0
	v_rcp_f32_e32 v35, v34
	s_nop 0
	v_fma_f32 v36, -v34, v35, 1.0
	v_fmac_f32_e32 v35, v36, v35
	v_div_scale_f32 v36, vcc, 1.0, v33, 1.0
	v_mul_f32_e32 v37, v36, v35
	v_fma_f32 v38, -v34, v37, v36
	v_fmac_f32_e32 v37, v38, v35
	v_fma_f32 v34, -v34, v37, v36
	v_add_u32_e32 v38, s9, v32
	v_div_fmas_f32 v34, v34, v35, v37
	v_mov_b64_e32 v[36:37], s[20:21]
	v_ashrrev_i32_e32 v39, 31, v38
	v_div_fixup_f32 v34, v34, v33, 1.0
	v_mad_i64_i32 v[36:37], s[10:11], v32, s84, v[36:37]
	v_lshlrev_b64 v[38:39], 11, v[38:39]
	v_lshl_add_u64 v[36:37], v[142:143], 1, v[36:37]
	v_lshl_add_u64 v[38:39], s[22:23], 0, v[38:39]
	v_pk_mul_f32 v[30:31], v[30:31], v[34:35] op_sel_hi:[1,0]
	v_pk_mul_f32 v[28:29], v[28:29], v[34:35] op_sel_hi:[1,0]
	v_pk_mul_f32 v[26:27], v[26:27], v[34:35] op_sel_hi:[1,0]
	v_pk_mul_f32 v[24:25], v[24:25], v[34:35] op_sel_hi:[1,0]
	s_and_b64 vcc, exec, s[40:41]
	v_cvt_pk_bf16_f32 v40, v28, v29
	v_cvt_pk_bf16_f32 v41, v30, v31
	v_cvt_pk_bf16_f32 v42, v24, v25
	v_cvt_pk_bf16_f32 v43, v26, v27
	global_store_dwordx4 v[36:37], v[40:43], off
	s_cbranch_vccnz .LBB0_254
	s_nop 0
	v_lshl_add_u64 v[40:41], v[140:141], 2, v[38:39]
	global_store_dwordx4 v[40:41], v[28:31], off nt
	global_store_dwordx4 v[40:41], v[24:27], off offset:16 nt

.LBB0_258:
	s_nop 1
	v_mov_b32_e32 v17, v170
	s_nop 0
	v_add_u32_e32 v16, 0xb0, v144
	v_fmamk_f32 v17, v17, 0x3a800000, v235
	v_cmp_gt_f32_e32 vcc, s73, v17
	v_mul_f32_e32 v18, 0x4f800000, v17
	s_nop 0
	v_cndmask_b32_e32 v17, v17, v18, vcc
	v_sqrt_f32_e32 v18, v17
	s_nop 0
	v_add_u32_e32 v19, -1, v18
	v_fma_f32 v20, -v19, v18, v17
	v_cmp_ge_f32_e64 s[42:43], 0, v20
	v_add_u32_e32 v20, 1, v18
	s_nop 0
	v_cndmask_b32_e64 v19, v18, v19, s[42:43]
	v_fma_f32 v18, -v20, v18, v17
	v_cmp_lt_f32_e64 s[42:43], 0, v18
	s_nop 1
	v_cndmask_b32_e64 v18, v19, v20, s[42:43]
	v_mul_f32_e32 v19, 0x37800000, v18
	v_cndmask_b32_e32 v18, v18, v19, vcc
	v_cmp_class_f32_e32 vcc, v17, v236
	s_nop 1
	v_cndmask_b32_e32 v17, v18, v17, vcc
	v_div_scale_f32 v18, s[10:11], v17, v17, 1.0
	v_rcp_f32_e32 v19, v18
	s_nop 0
	v_fma_f32 v20, -v18, v19, 1.0
	v_fmac_f32_e32 v19, v20, v19
	v_div_scale_f32 v20, vcc, 1.0, v17, 1.0
	v_mul_f32_e32 v21, v20, v19
	v_fma_f32 v22, -v18, v21, v20
	v_fmac_f32_e32 v21, v22, v19
	v_fma_f32 v18, -v18, v21, v20
	v_add_u32_e32 v22, s9, v16
	v_div_fmas_f32 v18, v18, v19, v21
	v_mov_b64_e32 v[20:21], s[20:21]
	v_ashrrev_i32_e32 v23, 31, v22
	v_div_fixup_f32 v18, v18, v17, 1.0
	v_mad_i64_i32 v[20:21], s[10:11], v16, s84, v[20:21]
	v_lshlrev_b64 v[22:23], 11, v[22:23]
	v_lshl_add_u64 v[20:21], v[142:143], 1, v[20:21]
	v_lshl_add_u64 v[22:23], s[22:23], 0, v[22:23]
	v_pk_mul_f32 v[14:15], v[14:15], v[18:19] op_sel_hi:[1,0]
	v_pk_mul_f32 v[12:13], v[12:13], v[18:19] op_sel_hi:[1,0]
	v_pk_mul_f32 v[10:11], v[10:11], v[18:19] op_sel_hi:[1,0]
	v_pk_mul_f32 v[8:9], v[8:9], v[18:19] op_sel_hi:[1,0]
	s_and_b64 vcc, exec, s[40:41]
	v_cvt_pk_bf16_f32 v24, v12, v13
	v_cvt_pk_bf16_f32 v25, v14, v15
	v_cvt_pk_bf16_f32 v26, v8, v9
	v_cvt_pk_bf16_f32 v27, v10, v11
	global_store_dwordx4 v[20:21], v[24:27], off
	s_cbranch_vccnz .LBB0_260
	s_nop 0
	v_lshl_add_u64 v[24:25], v[140:141], 2, v[22:23]
	global_store_dwordx4 v[24:25], v[12:15], off nt
	global_store_dwordx4 v[24:25], v[8:11], off offset:16 nt

.LBB0_1147:
	v_lshl_add_u32 v144, s22, 8, v149
	v_ashrrev_i32_e32 v145, 31, v144
	v_lshl_add_u64 v[138:139], v[144:145], 2, s[34:35]
	global_load_dword v142, v[138:139], off
	global_load_dword v164, v[138:139], off offset:64
	global_load_dword v165, v[138:139], off offset:128
	global_load_dword v166, v[138:139], off offset:192
	global_load_dword v167, v[138:139], off offset:512
	global_load_dword v168, v[138:139], off offset:576
	global_load_dword v169, v[138:139], off offset:640
	global_load_dword v170, v[138:139], off offset:704
	v_lshl_or_b32 v140, s4, 8, v151
	v_ashrrev_i32_e32 v141, 31, v140
	s_mov_b64 s[22:23], -1
	s_waitcnt vmcnt(0)
	v_fmamk_f32 v142, v142, 0x3a800000, v235
	v_cmp_gt_f32_e32 vcc, s73, v142
	v_mul_f32_e32 v143, 0x4f800000, v142
	s_nop 0
	v_cndmask_b32_e32 v142, v142, v143, vcc
	v_sqrt_f32_e32 v143, v142
	s_nop 0
	v_add_u32_e32 v146, -1, v143
	v_fma_f32 v153, -v146, v143, v142
	v_cmp_ge_f32_e64 s[40:41], 0, v153
	v_add_u32_e32 v153, 1, v143
	s_nop 0
	v_cndmask_b32_e64 v146, v143, v146, s[40:41]
	v_fma_f32 v143, -v153, v143, v142
	v_cmp_lt_f32_e64 s[40:41], 0, v143
	s_nop 1
	v_cndmask_b32_e64 v143, v146, v153, s[40:41]
	v_mul_f32_e32 v146, 0x37800000, v143
	v_cndmask_b32_e32 v143, v143, v146, vcc
	v_cmp_class_f32_e32 vcc, v142, v236
	s_nop 1
	v_cndmask_b32_e32 v142, v143, v142, vcc
	v_div_scale_f32 v143, s[4:5], v142, v142, 1.0
	v_rcp_f32_e32 v146, v143
	s_nop 0
	v_fma_f32 v153, -v143, v146, 1.0
	v_fmac_f32_e32 v146, v153, v146
	v_div_scale_f32 v153, vcc, 1.0, v142, 1.0
	v_mul_f32_e32 v154, v153, v146
	v_fma_f32 v155, -v143, v154, v153
	v_fmac_f32_e32 v154, v155, v146
	v_fma_f32 v143, -v143, v154, v153
	v_div_fmas_f32 v143, v143, v146, v154
	v_div_fixup_f32 v146, v143, v142, 1.0
	v_pk_mul_f32 v[120:121], v[120:121], v[146:147] op_sel_hi:[1,0]
	v_pk_mul_f32 v[124:125], v[124:125], v[146:147] op_sel_hi:[1,0]
	v_pk_mul_f32 v[122:123], v[122:123], v[146:147] op_sel_hi:[1,0]
	v_max_f32_e32 v120, 0, v120
	v_lshlrev_b64 v[142:143], 13, v[144:145]
	v_pk_mul_f32 v[126:127], v[126:127], v[146:147] op_sel_hi:[1,0]
	v_mul_f32_e32 v145, v120, v120
	v_max_f32_e32 v120, 0, v125
	v_max_f32_e32 v121, 0, v121
	v_max_f32_e32 v122, 0, v122
	v_lshl_add_u64 v[154:155], s[36:37], 0, v[142:143]
	v_lshlrev_b64 v[142:143], 1, v[140:141]
	v_max_f32_e32 v124, 0, v124
	v_mul_f32_e32 v120, v120, v120
	v_mul_f32_e32 v125, v121, v121
	v_max_f32_e32 v121, 0, v126
	v_mul_f32_e32 v126, v122, v122
	v_max_f32_e32 v122, 0, v127
	v_max_f32_e32 v123, 0, v123
	v_pk_mul_f32 v[114:115], v[114:115], v[146:147] op_sel_hi:[1,0]
	v_pk_mul_f32 v[112:113], v[112:113], v[146:147] op_sel_hi:[1,0]
	v_lshl_add_u64 v[140:141], v[154:155], 0, v[142:143]
	v_mul_f32_e32 v124, v124, v124
	v_mul_f32_e32 v121, v121, v121
	v_mul_f32_e32 v122, v122, v122
	v_mul_f32_e32 v123, v123, v123
	v_cvt_pk_bf16_f32 v120, v124, v120
	v_pk_mul_f32 v[118:119], v[118:119], v[146:147] op_sel_hi:[1,0]
	v_pk_mul_f32 v[116:117], v[116:117], v[146:147] op_sel_hi:[1,0]
	v_max_f32_e32 v112, 0, v112
	v_max_f32_e32 v113, 0, v113
	v_max_f32_e32 v114, 0, v114
	v_cvt_pk_bf16_f32 v121, v121, v122
	v_cvt_pk_bf16_f32 v122, v145, v125
	v_cvt_pk_bf16_f32 v123, v126, v123
	global_store_dwordx4 v[140:141], v[120:123], off
	v_max_f32_e32 v115, 0, v115
	v_max_f32_e32 v116, 0, v116
	v_mul_f32_e32 v120, v112, v112
	v_max_f32_e32 v112, 0, v117
	v_mul_f32_e32 v117, v113, v113
	v_max_f32_e32 v113, 0, v118
	v_mul_f32_e32 v118, v114, v114
	v_max_f32_e32 v114, 0, v119
	v_mul_f32_e32 v112, v112, v112
	v_mul_f32_e32 v113, v113, v113
	v_mul_f32_e32 v114, v114, v114
	v_mul_f32_e32 v115, v115, v115
	v_mul_f32_e32 v116, v116, v116
	v_cvt_pk_bf16_f32 v112, v116, v112
	v_cvt_pk_bf16_f32 v113, v113, v114
	v_cvt_pk_bf16_f32 v114, v120, v117
	v_cvt_pk_bf16_f32 v115, v118, v115
	global_store_dwordx4 v[140:141], v[112:115], off offset:256
	s_nop 1
	v_mov_b32_e32 v112, v164
	s_nop 0
	v_or_b32_e32 v114, 16, v144
	v_ashrrev_i32_e32 v115, 31, v114
	v_lshlrev_b64 v[114:115], 13, v[114:115]
	v_lshl_add_u64 v[114:115], s[36:37], 0, v[114:115]
	v_lshl_add_u64 v[114:115], v[114:115], 0, v[142:143]
	v_fmamk_f32 v112, v112, 0x3a800000, v235
	v_cmp_gt_f32_e32 vcc, s73, v112
	v_mul_f32_e32 v113, 0x4f800000, v112
	s_nop 0
	v_cndmask_b32_e32 v112, v112, v113, vcc
	v_sqrt_f32_e32 v113, v112
	s_nop 0
	v_add_u32_e32 v116, -1, v113
	v_fma_f32 v117, -v116, v113, v112
	v_cmp_ge_f32_e64 s[40:41], 0, v117
	v_add_u32_e32 v117, 1, v113
	s_nop 0
	v_cndmask_b32_e64 v116, v113, v116, s[40:41]
	v_fma_f32 v113, -v117, v113, v112
	v_cmp_lt_f32_e64 s[40:41], 0, v113
	s_nop 1
	v_cndmask_b32_e64 v113, v116, v117, s[40:41]
	v_mul_f32_e32 v116, 0x37800000, v113
	v_cndmask_b32_e32 v113, v113, v116, vcc
	v_cmp_class_f32_e32 vcc, v112, v236
	s_nop 1
	v_cndmask_b32_e32 v112, v113, v112, vcc
	v_div_scale_f32 v113, s[4:5], v112, v112, 1.0
	v_rcp_f32_e32 v116, v113
	s_nop 0
	v_fma_f32 v117, -v113, v116, 1.0
	v_fmac_f32_e32 v116, v117, v116
	v_div_scale_f32 v117, vcc, 1.0, v112, 1.0
	v_mul_f32_e32 v118, v117, v116
	v_fma_f32 v119, -v113, v118, v117
	v_fmac_f32_e32 v118, v119, v116
	v_fma_f32 v113, -v113, v118, v117
	v_div_fmas_f32 v113, v113, v116, v118
	v_div_fixup_f32 v112, v113, v112, 1.0
	v_pk_mul_f32 v[104:105], v[104:105], v[112:113] op_sel_hi:[1,0]
	v_pk_mul_f32 v[108:109], v[108:109], v[112:113] op_sel_hi:[1,0]
	v_pk_mul_f32 v[106:107], v[106:107], v[112:113] op_sel_hi:[1,0]
	v_max_f32_e32 v104, 0, v104
	v_pk_mul_f32 v[110:111], v[110:111], v[112:113] op_sel_hi:[1,0]
	v_mul_f32_e32 v113, v104, v104
	v_max_f32_e32 v104, 0, v109
	v_max_f32_e32 v105, 0, v105
	v_max_f32_e32 v106, 0, v106
	v_max_f32_e32 v108, 0, v108
	v_mul_f32_e32 v104, v104, v104
	v_mul_f32_e32 v109, v105, v105
	v_max_f32_e32 v105, 0, v110
	v_mul_f32_e32 v110, v106, v106
	v_max_f32_e32 v106, 0, v111
	v_max_f32_e32 v107, 0, v107
	v_pk_mul_f32 v[98:99], v[98:99], v[112:113] op_sel_hi:[1,0]
	v_pk_mul_f32 v[96:97], v[96:97], v[112:113] op_sel_hi:[1,0]
	v_mul_f32_e32 v108, v108, v108
	v_mul_f32_e32 v105, v105, v105
	v_mul_f32_e32 v106, v106, v106
	v_mul_f32_e32 v107, v107, v107
	v_cvt_pk_bf16_f32 v104, v108, v104
	v_pk_mul_f32 v[102:103], v[102:103], v[112:113] op_sel_hi:[1,0]
	v_pk_mul_f32 v[100:101], v[100:101], v[112:113] op_sel_hi:[1,0]
	v_max_f32_e32 v96, 0, v96
	v_max_f32_e32 v97, 0, v97
	v_max_f32_e32 v98, 0, v98
	v_cvt_pk_bf16_f32 v105, v105, v106
	v_cvt_pk_bf16_f32 v106, v113, v109
	v_cvt_pk_bf16_f32 v107, v110, v107
	global_store_dwordx4 v[114:115], v[104:107], off
	v_max_f32_e32 v99, 0, v99
	v_max_f32_e32 v100, 0, v100
	v_mul_f32_e32 v104, v96, v96
	v_max_f32_e32 v96, 0, v101
	v_mul_f32_e32 v101, v97, v97
	v_max_f32_e32 v97, 0, v102
	v_mul_f32_e32 v102, v98, v98
	v_max_f32_e32 v98, 0, v103
	v_mul_f32_e32 v96, v96, v96
	v_mul_f32_e32 v97, v97, v97
	v_mul_f32_e32 v98, v98, v98
	v_mul_f32_e32 v99, v99, v99
	v_mul_f32_e32 v100, v100, v100
	v_cvt_pk_bf16_f32 v96, v100, v96
	v_cvt_pk_bf16_f32 v97, v97, v98
	v_cvt_pk_bf16_f32 v98, v104, v101
	v_cvt_pk_bf16_f32 v99, v102, v99
	global_store_dwordx4 v[114:115], v[96:99], off offset:256
	s_nop 1
	v_mov_b32_e32 v96, v165
	s_nop 0
	v_or_b32_e32 v98, 32, v144
	v_ashrrev_i32_e32 v99, 31, v98
	v_lshlrev_b64 v[98:99], 13, v[98:99]
	v_lshl_add_u64 v[98:99], s[36:37], 0, v[98:99]
	v_lshl_add_u64 v[98:99], v[98:99], 0, v[142:143]
	v_fmamk_f32 v96, v96, 0x3a800000, v235
	v_cmp_gt_f32_e32 vcc, s73, v96
	v_mul_f32_e32 v97, 0x4f800000, v96
	s_nop 0
	v_cndmask_b32_e32 v96, v96, v97, vcc
	v_sqrt_f32_e32 v97, v96
	s_nop 0
	v_add_u32_e32 v100, -1, v97
	v_fma_f32 v101, -v100, v97, v96
	v_cmp_ge_f32_e64 s[40:41], 0, v101
	v_add_u32_e32 v101, 1, v97
	s_nop 0
	v_cndmask_b32_e64 v100, v97, v100, s[40:41]
	v_fma_f32 v97, -v101, v97, v96
	v_cmp_lt_f32_e64 s[40:41], 0, v97
	s_nop 1
	v_cndmask_b32_e64 v97, v100, v101, s[40:41]
	v_mul_f32_e32 v100, 0x37800000, v97
	v_cndmask_b32_e32 v97, v97, v100, vcc
	v_cmp_class_f32_e32 vcc, v96, v236
	s_nop 1
	v_cndmask_b32_e32 v96, v97, v96, vcc
	v_div_scale_f32 v97, s[4:5], v96, v96, 1.0
	v_rcp_f32_e32 v100, v97
	s_nop 0
	v_fma_f32 v101, -v97, v100, 1.0
	v_fmac_f32_e32 v100, v101, v100
	v_div_scale_f32 v101, vcc, 1.0, v96, 1.0
	v_mul_f32_e32 v102, v101, v100
	v_fma_f32 v103, -v97, v102, v101
	v_fmac_f32_e32 v102, v103, v100
	v_fma_f32 v97, -v97, v102, v101
	v_div_fmas_f32 v97, v97, v100, v102
	v_div_fixup_f32 v96, v97, v96, 1.0
	v_pk_mul_f32 v[88:89], v[88:89], v[96:97] op_sel_hi:[1,0]
	v_pk_mul_f32 v[92:93], v[92:93], v[96:97] op_sel_hi:[1,0]
	v_pk_mul_f32 v[90:91], v[90:91], v[96:97] op_sel_hi:[1,0]
	v_max_f32_e32 v88, 0, v88
	v_pk_mul_f32 v[94:95], v[94:95], v[96:97] op_sel_hi:[1,0]
	v_mul_f32_e32 v97, v88, v88
	v_max_f32_e32 v88, 0, v93
	v_max_f32_e32 v89, 0, v89
	v_max_f32_e32 v90, 0, v90
	v_max_f32_e32 v92, 0, v92
	v_mul_f32_e32 v88, v88, v88
	v_mul_f32_e32 v93, v89, v89
	v_max_f32_e32 v89, 0, v94
	v_mul_f32_e32 v94, v90, v90
	v_max_f32_e32 v90, 0, v95
	v_max_f32_e32 v91, 0, v91
	v_pk_mul_f32 v[82:83], v[82:83], v[96:97] op_sel_hi:[1,0]
	v_pk_mul_f32 v[80:81], v[80:81], v[96:97] op_sel_hi:[1,0]
	v_mul_f32_e32 v92, v92, v92
	v_mul_f32_e32 v89, v89, v89
	v_mul_f32_e32 v90, v90, v90
	v_mul_f32_e32 v91, v91, v91
	v_cvt_pk_bf16_f32 v88, v92, v88
	v_pk_mul_f32 v[86:87], v[86:87], v[96:97] op_sel_hi:[1,0]
	v_pk_mul_f32 v[84:85], v[84:85], v[96:97] op_sel_hi:[1,0]
	v_max_f32_e32 v80, 0, v80
	v_max_f32_e32 v81, 0, v81
	v_max_f32_e32 v82, 0, v82
	v_cvt_pk_bf16_f32 v89, v89, v90
	v_cvt_pk_bf16_f32 v90, v97, v93
	v_cvt_pk_bf16_f32 v91, v94, v91
	global_store_dwordx4 v[98:99], v[88:91], off
	v_max_f32_e32 v83, 0, v83
	v_max_f32_e32 v84, 0, v84
	v_mul_f32_e32 v88, v80, v80
	v_max_f32_e32 v80, 0, v85
	v_mul_f32_e32 v85, v81, v81
	v_max_f32_e32 v81, 0, v86
	v_mul_f32_e32 v86, v82, v82
	v_max_f32_e32 v82, 0, v87
	v_mul_f32_e32 v80, v80, v80
	v_mul_f32_e32 v81, v81, v81
	v_mul_f32_e32 v82, v82, v82
	v_mul_f32_e32 v83, v83, v83
	v_mul_f32_e32 v84, v84, v84
	v_cvt_pk_bf16_f32 v80, v84, v80
	v_cvt_pk_bf16_f32 v81, v81, v82
	v_cvt_pk_bf16_f32 v82, v88, v85
	v_cvt_pk_bf16_f32 v83, v86, v83
	global_store_dwordx4 v[98:99], v[80:83], off offset:256
	s_nop 1
	v_mov_b32_e32 v80, v166
	s_nop 0
	v_or_b32_e32 v82, 48, v144
	v_ashrrev_i32_e32 v83, 31, v82
	v_lshlrev_b64 v[82:83], 13, v[82:83]
	v_lshl_add_u64 v[82:83], s[36:37], 0, v[82:83]
	v_lshl_add_u64 v[82:83], v[82:83], 0, v[142:143]
	v_fmamk_f32 v80, v80, 0x3a800000, v235
	v_cmp_gt_f32_e32 vcc, s73, v80
	v_mul_f32_e32 v81, 0x4f800000, v80
	s_nop 0
	v_cndmask_b32_e32 v80, v80, v81, vcc
	v_sqrt_f32_e32 v81, v80
	s_nop 0
	v_add_u32_e32 v84, -1, v81
	v_fma_f32 v85, -v84, v81, v80
	v_cmp_ge_f32_e64 s[40:41], 0, v85
	v_add_u32_e32 v85, 1, v81
	s_nop 0
	v_cndmask_b32_e64 v84, v81, v84, s[40:41]
	v_fma_f32 v81, -v85, v81, v80
	v_cmp_lt_f32_e64 s[40:41], 0, v81
	s_nop 1
	v_cndmask_b32_e64 v81, v84, v85, s[40:41]
	v_mul_f32_e32 v84, 0x37800000, v81
	v_cndmask_b32_e32 v81, v81, v84, vcc
	v_cmp_class_f32_e32 vcc, v80, v236
	s_nop 1
	v_cndmask_b32_e32 v80, v81, v80, vcc
	v_div_scale_f32 v81, s[4:5], v80, v80, 1.0
	v_rcp_f32_e32 v84, v81
	s_nop 0
	v_fma_f32 v85, -v81, v84, 1.0
	v_fmac_f32_e32 v84, v85, v84
	v_div_scale_f32 v85, vcc, 1.0, v80, 1.0
	v_mul_f32_e32 v86, v85, v84
	v_fma_f32 v87, -v81, v86, v85
	v_fmac_f32_e32 v86, v87, v84
	v_fma_f32 v81, -v81, v86, v85
	v_div_fmas_f32 v81, v81, v84, v86
	v_div_fixup_f32 v80, v81, v80, 1.0
	v_pk_mul_f32 v[72:73], v[72:73], v[80:81] op_sel_hi:[1,0]
	v_pk_mul_f32 v[76:77], v[76:77], v[80:81] op_sel_hi:[1,0]
	v_pk_mul_f32 v[74:75], v[74:75], v[80:81] op_sel_hi:[1,0]
	v_max_f32_e32 v72, 0, v72
	v_pk_mul_f32 v[78:79], v[78:79], v[80:81] op_sel_hi:[1,0]
	v_mul_f32_e32 v81, v72, v72
	v_max_f32_e32 v72, 0, v77
	v_max_f32_e32 v73, 0, v73
	v_max_f32_e32 v74, 0, v74
	v_max_f32_e32 v76, 0, v76
	v_mul_f32_e32 v72, v72, v72
	v_mul_f32_e32 v77, v73, v73
	v_max_f32_e32 v73, 0, v78
	v_mul_f32_e32 v78, v74, v74
	v_max_f32_e32 v74, 0, v79
	v_max_f32_e32 v75, 0, v75
	v_pk_mul_f32 v[66:67], v[66:67], v[80:81] op_sel_hi:[1,0]
	v_pk_mul_f32 v[64:65], v[64:65], v[80:81] op_sel_hi:[1,0]
	v_mul_f32_e32 v76, v76, v76
	v_mul_f32_e32 v73, v73, v73
	v_mul_f32_e32 v74, v74, v74
	v_mul_f32_e32 v75, v75, v75
	v_cvt_pk_bf16_f32 v72, v76, v72
	v_pk_mul_f32 v[70:71], v[70:71], v[80:81] op_sel_hi:[1,0]
	v_pk_mul_f32 v[68:69], v[68:69], v[80:81] op_sel_hi:[1,0]
	v_max_f32_e32 v64, 0, v64
	v_max_f32_e32 v65, 0, v65
	v_max_f32_e32 v66, 0, v66
	v_cvt_pk_bf16_f32 v73, v73, v74
	v_cvt_pk_bf16_f32 v74, v81, v77
	v_cvt_pk_bf16_f32 v75, v78, v75
	global_store_dwordx4 v[82:83], v[72:75], off
	v_max_f32_e32 v67, 0, v67
	v_max_f32_e32 v68, 0, v68
	v_mul_f32_e32 v72, v64, v64
	v_max_f32_e32 v64, 0, v69
	v_mul_f32_e32 v69, v65, v65
	v_max_f32_e32 v65, 0, v70
	v_mul_f32_e32 v70, v66, v66
	v_max_f32_e32 v66, 0, v71
	v_mul_f32_e32 v64, v64, v64
	v_mul_f32_e32 v65, v65, v65
	v_mul_f32_e32 v66, v66, v66
	v_mul_f32_e32 v67, v67, v67
	v_mul_f32_e32 v68, v68, v68
	v_cvt_pk_bf16_f32 v64, v68, v64
	v_cvt_pk_bf16_f32 v65, v65, v66
	v_cvt_pk_bf16_f32 v66, v72, v69
	v_cvt_pk_bf16_f32 v67, v70, v67
	global_store_dwordx4 v[82:83], v[64:67], off offset:256
	s_nop 1
	v_mov_b32_e32 v64, v167
	v_fmamk_f32 v64, v64, 0x3a800000, v235
	v_cmp_gt_f32_e32 vcc, s73, v64
	v_mul_f32_e32 v65, 0x4f800000, v64
	s_nop 0
	v_cndmask_b32_e32 v64, v64, v65, vcc
	v_sqrt_f32_e32 v65, v64
	s_nop 0
	v_add_u32_e32 v66, -1, v65
	v_fma_f32 v67, -v66, v65, v64
	v_cmp_ge_f32_e64 s[40:41], 0, v67
	v_add_u32_e32 v67, 1, v65
	s_nop 0
	v_cndmask_b32_e64 v66, v65, v66, s[40:41]
	v_fma_f32 v65, -v67, v65, v64
	v_cmp_lt_f32_e64 s[40:41], 0, v65
	s_nop 1
	v_cndmask_b32_e64 v65, v66, v67, s[40:41]
	v_mul_f32_e32 v66, 0x37800000, v65
	v_cndmask_b32_e32 v65, v65, v66, vcc
	v_cmp_class_f32_e32 vcc, v64, v236
	s_nop 1
	v_cndmask_b32_e32 v64, v65, v64, vcc
	v_div_scale_f32 v65, s[4:5], v64, v64, 1.0
	v_rcp_f32_e32 v66, v65
	s_mov_b64 s[4:5], 0x100000
	v_fma_f32 v67, -v65, v66, 1.0
	v_fmac_f32_e32 v66, v67, v66
	v_div_scale_f32 v67, vcc, 1.0, v64, 1.0
	v_mul_f32_e32 v68, v67, v66
	v_fma_f32 v69, -v65, v68, v67
	v_fmac_f32_e32 v68, v69, v66
	v_fma_f32 v65, -v65, v68, v67
	v_div_fmas_f32 v65, v65, v66, v68
	v_div_fixup_f32 v66, v65, v64, 1.0
	v_pk_mul_f32 v[56:57], v[56:57], v[66:67] op_sel_hi:[1,0]
	v_pk_mul_f32 v[60:61], v[60:61], v[66:67] op_sel_hi:[1,0]
	v_pk_mul_f32 v[58:59], v[58:59], v[66:67] op_sel_hi:[1,0]
	v_max_f32_e32 v56, 0, v56
	v_pk_mul_f32 v[62:63], v[62:63], v[66:67] op_sel_hi:[1,0]
	v_max_f32_e32 v60, 0, v60
	v_mul_f32_e32 v67, v56, v56
	v_max_f32_e32 v56, 0, v61
	v_max_f32_e32 v57, 0, v57
	v_max_f32_e32 v58, 0, v58
	v_lshl_add_u64 v[64:65], v[140:141], 0, s[4:5]
	v_mul_f32_e32 v60, v60, v60
	v_mul_f32_e32 v56, v56, v56
	v_mul_f32_e32 v61, v57, v57
	v_max_f32_e32 v57, 0, v62
	v_mul_f32_e32 v62, v58, v58
	v_max_f32_e32 v58, 0, v63
	s_mov_b32 s4, 0x100000
	v_mul_f32_e32 v57, v57, v57
	v_max_f32_e32 v59, 0, v59
	v_mul_f32_e32 v58, v58, v58
	v_cvt_pk_bf16_f32 v56, v60, v56
	v_add_co_u32_e32 v60, vcc, s4, v140
	v_pk_mul_f32 v[50:51], v[50:51], v[66:67] op_sel_hi:[1,0]
	v_pk_mul_f32 v[48:49], v[48:49], v[66:67] op_sel_hi:[1,0]
	v_mul_f32_e32 v59, v59, v59
	v_cvt_pk_bf16_f32 v57, v57, v58
	v_cvt_pk_bf16_f32 v58, v67, v61
	v_addc_co_u32_e32 v61, vcc, 0, v141, vcc
	v_pk_mul_f32 v[54:55], v[54:55], v[66:67] op_sel_hi:[1,0]
	v_pk_mul_f32 v[52:53], v[52:53], v[66:67] op_sel_hi:[1,0]
	v_max_f32_e32 v48, 0, v48
	v_max_f32_e32 v49, 0, v49
	v_max_f32_e32 v50, 0, v50
	v_cvt_pk_bf16_f32 v59, v62, v59
	global_store_dwordx4 v[60:61], v[56:59], off
	v_max_f32_e32 v51, 0, v51
	v_max_f32_e32 v52, 0, v52
	v_mul_f32_e32 v56, v48, v48
	v_max_f32_e32 v48, 0, v53
	v_mul_f32_e32 v53, v49, v49
	v_max_f32_e32 v49, 0, v54
	v_mul_f32_e32 v54, v50, v50
	v_max_f32_e32 v50, 0, v55
	v_mul_f32_e32 v48, v48, v48
	v_mul_f32_e32 v49, v49, v49
	v_mul_f32_e32 v50, v50, v50
	v_mul_f32_e32 v51, v51, v51
	v_mul_f32_e32 v52, v52, v52
	v_cvt_pk_bf16_f32 v48, v52, v48
	v_cvt_pk_bf16_f32 v49, v49, v50
	v_cvt_pk_bf16_f32 v50, v56, v53
	v_cvt_pk_bf16_f32 v51, v54, v51
	global_store_dwordx4 v[64:65], v[48:51], off offset:256
	s_nop 1
	v_mov_b32_e32 v48, v168
	v_fmamk_f32 v48, v48, 0x3a800000, v235
	v_cmp_gt_f32_e32 vcc, s73, v48
	v_mul_f32_e32 v49, 0x4f800000, v48
	s_nop 0
	v_cndmask_b32_e32 v48, v48, v49, vcc
	v_sqrt_f32_e32 v49, v48
	s_nop 0
	v_add_u32_e32 v50, -1, v49
	v_fma_f32 v51, -v50, v49, v48
	v_cmp_ge_f32_e64 s[40:41], 0, v51
	v_add_u32_e32 v51, 1, v49
	s_nop 0
	v_cndmask_b32_e64 v50, v49, v50, s[40:41]
	v_fma_f32 v49, -v51, v49, v48
	v_cmp_lt_f32_e64 s[40:41], 0, v49
	s_nop 1
	v_cndmask_b32_e64 v49, v50, v51, s[40:41]
	v_mul_f32_e32 v50, 0x37800000, v49
	v_cndmask_b32_e32 v49, v49, v50, vcc
	v_cmp_class_f32_e32 vcc, v48, v236
	s_nop 1
	v_cndmask_b32_e32 v48, v49, v48, vcc
	v_div_scale_f32 v49, s[4:5], v48, v48, 1.0
	v_rcp_f32_e32 v50, v49
	s_mov_b64 s[4:5], 0x120000
	v_fma_f32 v51, -v49, v50, 1.0
	v_fmac_f32_e32 v50, v51, v50
	v_div_scale_f32 v51, vcc, 1.0, v48, 1.0
	v_mul_f32_e32 v52, v51, v50
	v_fma_f32 v53, -v49, v52, v51
	v_fmac_f32_e32 v52, v53, v50
	v_fma_f32 v49, -v49, v52, v51
	v_div_fmas_f32 v49, v49, v50, v52
	v_div_fixup_f32 v50, v49, v48, 1.0
	v_pk_mul_f32 v[40:41], v[40:41], v[50:51] op_sel_hi:[1,0]
	v_pk_mul_f32 v[44:45], v[44:45], v[50:51] op_sel_hi:[1,0]
	v_pk_mul_f32 v[42:43], v[42:43], v[50:51] op_sel_hi:[1,0]
	v_max_f32_e32 v40, 0, v40
	v_pk_mul_f32 v[46:47], v[46:47], v[50:51] op_sel_hi:[1,0]
	v_max_f32_e32 v44, 0, v44
	v_mul_f32_e32 v51, v40, v40
	v_max_f32_e32 v40, 0, v45
	v_max_f32_e32 v41, 0, v41
	v_max_f32_e32 v42, 0, v42
	v_lshl_add_u64 v[48:49], v[140:141], 0, s[4:5]
	v_mul_f32_e32 v44, v44, v44
	v_mul_f32_e32 v40, v40, v40
	v_mul_f32_e32 v45, v41, v41
	v_max_f32_e32 v41, 0, v46
	v_mul_f32_e32 v46, v42, v42
	v_max_f32_e32 v42, 0, v47
	s_mov_b32 s4, 0x120000
	v_mul_f32_e32 v41, v41, v41
	v_max_f32_e32 v43, 0, v43
	v_mul_f32_e32 v42, v42, v42
	v_cvt_pk_bf16_f32 v40, v44, v40
	v_add_co_u32_e32 v44, vcc, s4, v140
	v_pk_mul_f32 v[34:35], v[34:35], v[50:51] op_sel_hi:[1,0]
	v_pk_mul_f32 v[32:33], v[32:33], v[50:51] op_sel_hi:[1,0]
	v_mul_f32_e32 v43, v43, v43
	v_cvt_pk_bf16_f32 v41, v41, v42
	v_cvt_pk_bf16_f32 v42, v51, v45
	v_addc_co_u32_e32 v45, vcc, 0, v141, vcc
	v_pk_mul_f32 v[38:39], v[38:39], v[50:51] op_sel_hi:[1,0]
	v_pk_mul_f32 v[36:37], v[36:37], v[50:51] op_sel_hi:[1,0]
	v_max_f32_e32 v32, 0, v32
	v_max_f32_e32 v33, 0, v33
	v_max_f32_e32 v34, 0, v34
	v_cvt_pk_bf16_f32 v43, v46, v43
	global_store_dwordx4 v[44:45], v[40:43], off
	v_max_f32_e32 v35, 0, v35
	v_max_f32_e32 v36, 0, v36
	v_mul_f32_e32 v40, v32, v32
	v_max_f32_e32 v32, 0, v37
	v_mul_f32_e32 v37, v33, v33
	v_max_f32_e32 v33, 0, v38
	v_mul_f32_e32 v38, v34, v34
	v_max_f32_e32 v34, 0, v39
	v_mul_f32_e32 v32, v32, v32
	v_mul_f32_e32 v33, v33, v33
	v_mul_f32_e32 v34, v34, v34
	v_mul_f32_e32 v35, v35, v35
	v_mul_f32_e32 v36, v36, v36
	v_cvt_pk_bf16_f32 v32, v36, v32
	v_cvt_pk_bf16_f32 v33, v33, v34
	v_cvt_pk_bf16_f32 v34, v40, v37
	v_cvt_pk_bf16_f32 v35, v38, v35
	global_store_dwordx4 v[48:49], v[32:35], off offset:256
	s_nop 1
	v_mov_b32_e32 v32, v169
	v_fmamk_f32 v32, v32, 0x3a800000, v235
	v_cmp_gt_f32_e32 vcc, s73, v32
	v_mul_f32_e32 v33, 0x4f800000, v32
	s_nop 0
	v_cndmask_b32_e32 v32, v32, v33, vcc
	v_sqrt_f32_e32 v33, v32
	s_nop 0
	v_add_u32_e32 v34, -1, v33
	v_fma_f32 v35, -v34, v33, v32
	v_cmp_ge_f32_e64 s[40:41], 0, v35
	v_add_u32_e32 v35, 1, v33
	s_nop 0
	v_cndmask_b32_e64 v34, v33, v34, s[40:41]
	v_fma_f32 v33, -v35, v33, v32
	v_cmp_lt_f32_e64 s[40:41], 0, v33
	s_nop 1
	v_cndmask_b32_e64 v33, v34, v35, s[40:41]
	v_mul_f32_e32 v34, 0x37800000, v33
	v_cndmask_b32_e32 v33, v33, v34, vcc
	v_cmp_class_f32_e32 vcc, v32, v236
	s_nop 1
	v_cndmask_b32_e32 v32, v33, v32, vcc
	v_div_scale_f32 v33, s[4:5], v32, v32, 1.0
	v_rcp_f32_e32 v34, v33
	s_mov_b64 s[4:5], 0x140000
	v_fma_f32 v35, -v33, v34, 1.0
	v_fmac_f32_e32 v34, v35, v34
	v_div_scale_f32 v35, vcc, 1.0, v32, 1.0
	v_mul_f32_e32 v36, v35, v34
	v_fma_f32 v37, -v33, v36, v35
	v_fmac_f32_e32 v36, v37, v34
	v_fma_f32 v33, -v33, v36, v35
	v_div_fmas_f32 v33, v33, v34, v36
	v_div_fixup_f32 v34, v33, v32, 1.0
	v_pk_mul_f32 v[24:25], v[24:25], v[34:35] op_sel_hi:[1,0]
	v_pk_mul_f32 v[28:29], v[28:29], v[34:35] op_sel_hi:[1,0]
	v_pk_mul_f32 v[26:27], v[26:27], v[34:35] op_sel_hi:[1,0]
	v_max_f32_e32 v24, 0, v24
	v_pk_mul_f32 v[30:31], v[30:31], v[34:35] op_sel_hi:[1,0]
	v_max_f32_e32 v28, 0, v28
	v_mul_f32_e32 v35, v24, v24
	v_max_f32_e32 v24, 0, v29
	v_max_f32_e32 v25, 0, v25
	v_max_f32_e32 v26, 0, v26
	v_lshl_add_u64 v[32:33], v[140:141], 0, s[4:5]
	v_mul_f32_e32 v28, v28, v28
	v_mul_f32_e32 v24, v24, v24
	v_mul_f32_e32 v29, v25, v25
	v_max_f32_e32 v25, 0, v30
	v_mul_f32_e32 v30, v26, v26
	v_max_f32_e32 v26, 0, v31
	s_mov_b32 s4, 0x140000
	v_mul_f32_e32 v25, v25, v25
	v_max_f32_e32 v27, 0, v27
	v_mul_f32_e32 v26, v26, v26
	v_cvt_pk_bf16_f32 v24, v28, v24
	v_add_co_u32_e32 v28, vcc, s4, v140
	v_pk_mul_f32 v[18:19], v[18:19], v[34:35] op_sel_hi:[1,0]
	v_pk_mul_f32 v[16:17], v[16:17], v[34:35] op_sel_hi:[1,0]
	v_mul_f32_e32 v27, v27, v27
	v_cvt_pk_bf16_f32 v25, v25, v26
	v_cvt_pk_bf16_f32 v26, v35, v29
	v_addc_co_u32_e32 v29, vcc, 0, v141, vcc
	v_pk_mul_f32 v[22:23], v[22:23], v[34:35] op_sel_hi:[1,0]
	v_pk_mul_f32 v[20:21], v[20:21], v[34:35] op_sel_hi:[1,0]
	v_max_f32_e32 v16, 0, v16
	v_max_f32_e32 v17, 0, v17
	v_max_f32_e32 v18, 0, v18
	v_cvt_pk_bf16_f32 v27, v30, v27
	global_store_dwordx4 v[28:29], v[24:27], off
	v_max_f32_e32 v19, 0, v19
	v_max_f32_e32 v20, 0, v20
	v_mul_f32_e32 v24, v16, v16
	v_max_f32_e32 v16, 0, v21
	v_mul_f32_e32 v21, v17, v17
	v_max_f32_e32 v17, 0, v22
	v_mul_f32_e32 v22, v18, v18
	v_max_f32_e32 v18, 0, v23
	v_mul_f32_e32 v16, v16, v16
	v_mul_f32_e32 v17, v17, v17
	v_mul_f32_e32 v18, v18, v18
	v_mul_f32_e32 v19, v19, v19
	v_mul_f32_e32 v20, v20, v20
	v_cvt_pk_bf16_f32 v16, v20, v16
	v_cvt_pk_bf16_f32 v17, v17, v18
	v_cvt_pk_bf16_f32 v18, v24, v21
	v_cvt_pk_bf16_f32 v19, v22, v19
	global_store_dwordx4 v[32:33], v[16:19], off offset:256
	s_nop 1
	v_mov_b32_e32 v16, v170
	v_fmamk_f32 v16, v16, 0x3a800000, v235
	v_cmp_gt_f32_e32 vcc, s73, v16
	v_mul_f32_e32 v17, 0x4f800000, v16
	s_nop 0
	v_cndmask_b32_e32 v16, v16, v17, vcc
	v_sqrt_f32_e32 v17, v16
	s_nop 0
	v_add_u32_e32 v18, -1, v17
	v_fma_f32 v19, -v18, v17, v16
	v_cmp_ge_f32_e64 s[40:41], 0, v19
	v_add_u32_e32 v19, 1, v17
	s_nop 0
	v_cndmask_b32_e64 v18, v17, v18, s[40:41]
	v_fma_f32 v17, -v19, v17, v16
	v_cmp_lt_f32_e64 s[40:41], 0, v17
	s_nop 1
	v_cndmask_b32_e64 v17, v18, v19, s[40:41]
	v_mul_f32_e32 v18, 0x37800000, v17
	v_cndmask_b32_e32 v17, v17, v18, vcc
	v_cmp_class_f32_e32 vcc, v16, v236
	s_nop 1
	v_cndmask_b32_e32 v16, v17, v16, vcc
	v_div_scale_f32 v17, s[4:5], v16, v16, 1.0
	v_rcp_f32_e32 v18, v17
	s_mov_b64 s[4:5], 0x160000
	v_fma_f32 v19, -v17, v18, 1.0
	v_fmac_f32_e32 v18, v19, v18
	v_div_scale_f32 v19, vcc, 1.0, v16, 1.0
	v_mul_f32_e32 v20, v19, v18
	v_fma_f32 v21, -v17, v20, v19
	v_fmac_f32_e32 v20, v21, v18
	v_fma_f32 v17, -v17, v20, v19
	v_div_fmas_f32 v17, v17, v18, v20
	v_div_fixup_f32 v16, v17, v16, 1.0
	v_pk_mul_f32 v[8:9], v[8:9], v[16:17] op_sel_hi:[1,0]
	v_pk_mul_f32 v[12:13], v[12:13], v[16:17] op_sel_hi:[1,0]
	v_pk_mul_f32 v[10:11], v[10:11], v[16:17] op_sel_hi:[1,0]
	v_max_f32_e32 v8, 0, v8
	v_pk_mul_f32 v[14:15], v[14:15], v[16:17] op_sel_hi:[1,0]
	v_max_f32_e32 v12, 0, v12
	v_mul_f32_e32 v17, v8, v8
	v_max_f32_e32 v8, 0, v13
	v_max_f32_e32 v9, 0, v9
	v_max_f32_e32 v10, 0, v10
	v_lshl_add_u64 v[18:19], v[140:141], 0, s[4:5]
	v_mul_f32_e32 v12, v12, v12
	v_mul_f32_e32 v8, v8, v8
	v_mul_f32_e32 v13, v9, v9
	v_max_f32_e32 v9, 0, v14
	v_mul_f32_e32 v14, v10, v10
	v_max_f32_e32 v10, 0, v15
	s_mov_b32 s4, 0x160000
	v_mul_f32_e32 v9, v9, v9
	v_max_f32_e32 v11, 0, v11
	v_mul_f32_e32 v10, v10, v10
	v_cvt_pk_bf16_f32 v8, v12, v8
	v_add_co_u32_e32 v12, vcc, s4, v140
	v_pk_mul_f32 v[2:3], v[2:3], v[16:17] op_sel_hi:[1,0]
	v_pk_mul_f32 v[0:1], v[0:1], v[16:17] op_sel_hi:[1,0]
	v_mul_f32_e32 v11, v11, v11
	v_cvt_pk_bf16_f32 v9, v9, v10
	v_cvt_pk_bf16_f32 v10, v17, v13
	v_addc_co_u32_e32 v13, vcc, 0, v141, vcc
	v_pk_mul_f32 v[6:7], v[6:7], v[16:17] op_sel_hi:[1,0]
	v_pk_mul_f32 v[4:5], v[4:5], v[16:17] op_sel_hi:[1,0]
	v_max_f32_e32 v0, 0, v0
	v_max_f32_e32 v1, 0, v1
	v_max_f32_e32 v2, 0, v2
	v_cvt_pk_bf16_f32 v11, v14, v11
	global_store_dwordx4 v[12:13], v[8:11], off
	v_max_f32_e32 v3, 0, v3
	v_max_f32_e32 v4, 0, v4
	v_mul_f32_e32 v8, v0, v0
	v_max_f32_e32 v0, 0, v5
	v_mul_f32_e32 v5, v1, v1
	v_max_f32_e32 v1, 0, v6
	v_mul_f32_e32 v6, v2, v2
	v_max_f32_e32 v2, 0, v7
	v_mul_f32_e32 v0, v0, v0
	v_mul_f32_e32 v1, v1, v1
	v_mul_f32_e32 v2, v2, v2
	v_mul_f32_e32 v3, v3, v3
	s_andn2_b64 vcc, exec, s[38:39]
	v_mul_f32_e32 v4, v4, v4
	v_cvt_pk_bf16_f32 v0, v4, v0
	v_cvt_pk_bf16_f32 v1, v1, v2
	v_cvt_pk_bf16_f32 v2, v8, v5
	v_cvt_pk_bf16_f32 v3, v6, v3
	global_store_dwordx4 v[18:19], v[0:3], off offset:256
	s_cbranch_vccnz .LBB0_1136
	s_andn2_b64 vcc, exec, s[42:43]
	s_cbranch_vccnz .LBB0_1135
	s_barrier
	s_branch .LBB0_1135
